# baseline (speedup 1.0000x reference)
.LBB0_395:
	s_cmp_eq_u32 s56, 0
	s_cselect_b64 s[0:1], -1, 0
	s_or_b64 s[0:1], s[76:77], s[0:1]
	s_and_b64 vcc, exec, s[0:1]
	s_cbranch_vccnz .LBB0_397
	s_add_i32 s0, s86, 0xc000
	s_and_b32 s0, s0, 0xc000
	v_add_u32_e32 v0, s0, v234
	ds_read_b64_tr_b16 v[144:145], v0 offset:0x2000
	ds_read_b64_tr_b16 v[146:147], v0 offset:0x2800
	ds_read_b64_tr_b16 v[148:149], v0 offset:0x3000
	ds_read_b64_tr_b16 v[150:151], v0 offset:0x3800
	ds_read_b64_tr_b16 v[152:153], v0 offset:0x2200
	ds_read_b64_tr_b16 v[154:155], v0 offset:0x2a00
	ds_read_b64_tr_b16 v[156:157], v0 offset:0x3200
	ds_read_b64_tr_b16 v[158:159], v0 offset:0x3a00
	ds_read_b64_tr_b16 v[160:161], v0 offset:0x2400
	ds_read_b64_tr_b16 v[162:163], v0 offset:0x2c00
	ds_read_b64_tr_b16 v[164:165], v0 offset:0x3400
	ds_read_b64_tr_b16 v[166:167], v0 offset:0x3c00
	s_waitcnt lgkmcnt(10)
	s_nop 0
	v_mfma_f32_32x32x16_bf16 v[128:143], v[6:9], v[144:147], v[128:143]
	v_mfma_f32_32x32x16_bf16 v[96:111], v[2:5], v[144:147], v[96:111]
	ds_read_b64_tr_b16 v[168:169], v0 offset:0x2600
	ds_read_b64_tr_b16 v[170:171], v0 offset:0x2e00
	s_waitcnt lgkmcnt(10)
	v_mfma_f32_32x32x16_bf16 v[128:143], v[208:211], v[148:151], v[128:143]
	v_mfma_f32_32x32x16_bf16 v[96:111], v[10:13], v[148:151], v[96:111]
	ds_read_b64_tr_b16 v[172:173], v0 offset:0x3600
	ds_read_b64_tr_b16 v[174:175], v0 offset:0x3e00
	s_waitcnt lgkmcnt(10)
	v_mfma_f32_32x32x16_bf16 v[112:127], v[6:9], v[152:155], v[112:127]
	v_mfma_f32_32x32x16_bf16 v[80:95], v[2:5], v[152:155], v[80:95]
	s_waitcnt lgkmcnt(8)
	v_mfma_f32_32x32x16_bf16 v[112:127], v[208:211], v[156:159], v[112:127]
	v_mfma_f32_32x32x16_bf16 v[80:95], v[10:13], v[156:159], v[80:95]
	s_waitcnt lgkmcnt(6)
	v_mfma_f32_32x32x16_bf16 v[64:79], v[6:9], v[160:163], v[64:79]
	v_mfma_f32_32x32x16_bf16 v[32:47], v[2:5], v[160:163], v[32:47]
	s_waitcnt lgkmcnt(4)
	v_mfma_f32_32x32x16_bf16 v[64:79], v[208:211], v[164:167], v[64:79]
	v_mfma_f32_32x32x16_bf16 v[32:47], v[10:13], v[164:167], v[32:47]
	s_waitcnt lgkmcnt(2)
	v_mfma_f32_32x32x16_bf16 v[48:63], v[6:9], v[168:171], v[48:63]
	v_mfma_f32_32x32x16_bf16 v[16:31], v[2:5], v[168:171], v[16:31]
	s_waitcnt lgkmcnt(0)
	v_mfma_f32_32x32x16_bf16 v[48:63], v[208:211], v[172:175], v[48:63]
	v_mfma_f32_32x32x16_bf16 v[16:31], v[10:13], v[172:175], v[16:31]

.LBB0_413:
	v_add_u32_e32 v242, s27, v234
	ds_read_b64_tr_b16 v[144:145], v242 offset:0
	ds_read_b64_tr_b16 v[146:147], v242 offset:0x800
	ds_read_b64_tr_b16 v[148:149], v242 offset:0x1000
	ds_read_b64_tr_b16 v[150:151], v242 offset:0x1800
	ds_read_b64_tr_b16 v[152:153], v242 offset:0x200
	ds_read_b64_tr_b16 v[154:155], v242 offset:0xa00
	ds_read_b64_tr_b16 v[156:157], v242 offset:0x1200
	ds_read_b64_tr_b16 v[158:159], v242 offset:0x1a00
	ds_read_b64_tr_b16 v[160:161], v242 offset:0x400
	ds_read_b64_tr_b16 v[162:163], v242 offset:0xc00
	ds_read_b64_tr_b16 v[164:165], v242 offset:0x1400
	ds_read_b64_tr_b16 v[166:167], v242 offset:0x1c00
	s_waitcnt lgkmcnt(10)
	s_nop 0
	v_mfma_f32_32x32x16_bf16 v[128:143], v[216:219], v[144:147], v[128:143]
	v_mfma_f32_32x32x16_bf16 v[96:111], v[212:215], v[144:147], v[96:111]
	ds_read_b64_tr_b16 v[168:169], v242 offset:0x600
	ds_read_b64_tr_b16 v[170:171], v242 offset:0xe00
	s_waitcnt lgkmcnt(10)
	v_mfma_f32_32x32x16_bf16 v[128:143], v[224:227], v[148:151], v[128:143]
	v_mfma_f32_32x32x16_bf16 v[96:111], v[220:223], v[148:151], v[96:111]
	ds_read_b64_tr_b16 v[172:173], v242 offset:0x1600
	ds_read_b64_tr_b16 v[174:175], v242 offset:0x1e00
	s_waitcnt lgkmcnt(10)
	v_mfma_f32_32x32x16_bf16 v[112:127], v[216:219], v[152:155], v[112:127]
	v_mfma_f32_32x32x16_bf16 v[80:95], v[212:215], v[152:155], v[80:95]
	s_waitcnt lgkmcnt(8)
	v_mfma_f32_32x32x16_bf16 v[112:127], v[224:227], v[156:159], v[112:127]
	v_mfma_f32_32x32x16_bf16 v[80:95], v[220:223], v[156:159], v[80:95]
	ds_read_b128 v[144:147], v241 offset:0x2000
	ds_read_b128 v[148:151], v240 offset:0x2000
	ds_read_b128 v[152:155], v239 offset:0x2000
	ds_read_b128 v[156:159], v0 offset:0x2000
	s_waitcnt lgkmcnt(10)
	v_mfma_f32_32x32x16_bf16 v[64:79], v[216:219], v[160:163], v[64:79]
	v_mfma_f32_32x32x16_bf16 v[32:47], v[212:215], v[160:163], v[32:47]
	s_waitcnt lgkmcnt(8)
	v_mfma_f32_32x32x16_bf16 v[64:79], v[224:227], v[164:167], v[64:79]
	v_mfma_f32_32x32x16_bf16 v[32:47], v[220:223], v[164:167], v[32:47]
	s_waitcnt lgkmcnt(6)
	v_mfma_f32_32x32x16_bf16 v[48:63], v[216:219], v[168:171], v[48:63]
	v_mfma_f32_32x32x16_bf16 v[16:31], v[212:215], v[168:171], v[16:31]
	s_waitcnt lgkmcnt(4)
	v_mfma_f32_32x32x16_bf16 v[48:63], v[224:227], v[172:175], v[48:63]
	v_mfma_f32_32x32x16_bf16 v[16:31], v[220:223], v[172:175], v[16:31]
	s_waitcnt lgkmcnt(0)
	s_waitcnt lgkmcnt(0)
	v_mfma_f32_32x32x16_bf16 v[160:175], v[144:147], v[176:179], 0
	v_cmp_eq_f32_e32 vcc, 0, v238
	s_cmp_eq_u64 vcc, exec
	v_mfma_f32_32x32x16_bf16 v[160:175], v[148:151], v[180:183], v[160:175]
	v_mfma_f32_32x32x16_bf16 v[160:175], v[152:155], v[184:187], v[160:175]
	v_mfma_f32_32x32x16_bf16 v[160:175], v[156:159], v[188:191], v[160:175]
	s_cbranch_scc0 .LBB0_443

.LBB0_429:
	s_andn2_b64 vcc, exec, s[46:47]
	s_cbranch_vccnz .LBB0_388
	ds_read_b64_tr_b16 v[144:145], v242 offset:0x2000
	ds_read_b64_tr_b16 v[146:147], v242 offset:0x2800
	ds_read_b64_tr_b16 v[148:149], v242 offset:0x3000
	ds_read_b64_tr_b16 v[150:151], v242 offset:0x3800
	ds_read_b64_tr_b16 v[152:153], v242 offset:0x2200
	ds_read_b64_tr_b16 v[154:155], v242 offset:0x2a00
	ds_read_b64_tr_b16 v[156:157], v242 offset:0x3200
	ds_read_b64_tr_b16 v[158:159], v242 offset:0x3a00
	ds_read_b64_tr_b16 v[160:161], v242 offset:0x2400
	ds_read_b64_tr_b16 v[162:163], v242 offset:0x2c00
	ds_read_b64_tr_b16 v[164:165], v242 offset:0x3400
	ds_read_b64_tr_b16 v[166:167], v242 offset:0x3c00
	s_waitcnt lgkmcnt(10)
	s_nop 0
	v_mfma_f32_32x32x16_bf16 v[128:143], v[6:9], v[144:147], v[128:143]
	v_mfma_f32_32x32x16_bf16 v[96:111], v[2:5], v[144:147], v[96:111]
	ds_read_b64_tr_b16 v[168:169], v242 offset:0x2600
	ds_read_b64_tr_b16 v[170:171], v242 offset:0x2e00
	s_waitcnt lgkmcnt(10)
	v_mfma_f32_32x32x16_bf16 v[128:143], v[208:211], v[148:151], v[128:143]
	v_mfma_f32_32x32x16_bf16 v[96:111], v[10:13], v[148:151], v[96:111]
	ds_read_b64_tr_b16 v[172:173], v242 offset:0x3600
	ds_read_b64_tr_b16 v[174:175], v242 offset:0x3e00
	s_waitcnt lgkmcnt(10)
	v_mfma_f32_32x32x16_bf16 v[112:127], v[6:9], v[152:155], v[112:127]
	v_mfma_f32_32x32x16_bf16 v[80:95], v[2:5], v[152:155], v[80:95]
	s_waitcnt lgkmcnt(8)
	v_mfma_f32_32x32x16_bf16 v[112:127], v[208:211], v[156:159], v[112:127]
	v_mfma_f32_32x32x16_bf16 v[80:95], v[10:13], v[156:159], v[80:95]
	s_waitcnt lgkmcnt(6)
	v_mfma_f32_32x32x16_bf16 v[64:79], v[6:9], v[160:163], v[64:79]
	v_mfma_f32_32x32x16_bf16 v[32:47], v[2:5], v[160:163], v[32:47]
	s_waitcnt lgkmcnt(4)
	v_mfma_f32_32x32x16_bf16 v[64:79], v[208:211], v[164:167], v[64:79]
	v_mfma_f32_32x32x16_bf16 v[32:47], v[10:13], v[164:167], v[32:47]
	s_waitcnt lgkmcnt(2)
	v_mfma_f32_32x32x16_bf16 v[48:63], v[6:9], v[168:171], v[48:63]
	v_mfma_f32_32x32x16_bf16 v[16:31], v[2:5], v[168:171], v[16:31]
	s_waitcnt lgkmcnt(0)
	v_mfma_f32_32x32x16_bf16 v[48:63], v[208:211], v[172:175], v[48:63]
	v_mfma_f32_32x32x16_bf16 v[16:31], v[10:13], v[172:175], v[16:31]
	s_branch .LBB0_388

.LBB0_463:
	s_and_b64 vcc, exec, s[34:35]
	s_cbranch_vccz .LBB0_465
	s_cmp_lg_u32 0, -1
	s_cselect_b32 s0, 0, 0
	s_add_i32 s0, s0, 0xc000
	v_add_u32_e32 v0, s0, v232
	ds_read_b64_tr_b16 v[144:145], v0 offset:0x2000
	ds_read_b64_tr_b16 v[146:147], v0 offset:0x2800
	ds_read_b64_tr_b16 v[148:149], v0 offset:0x3000
	ds_read_b64_tr_b16 v[150:151], v0 offset:0x3800
	ds_read_b64_tr_b16 v[152:153], v0 offset:0x2200
	ds_read_b64_tr_b16 v[154:155], v0 offset:0x2a00
	ds_read_b64_tr_b16 v[156:157], v0 offset:0x3200
	ds_read_b64_tr_b16 v[158:159], v0 offset:0x3a00
	ds_read_b64_tr_b16 v[160:161], v0 offset:0x2400
	ds_read_b64_tr_b16 v[162:163], v0 offset:0x2c00
	ds_read_b64_tr_b16 v[164:165], v0 offset:0x3400
	ds_read_b64_tr_b16 v[166:167], v0 offset:0x3c00
	s_waitcnt lgkmcnt(10)
	s_nop 0
	v_mfma_f32_32x32x16_bf16 v[128:143], v[6:9], v[144:147], v[128:143]
	v_mfma_f32_32x32x16_bf16 v[96:111], v[2:5], v[144:147], v[96:111]
	ds_read_b64_tr_b16 v[168:169], v0 offset:0x2600
	ds_read_b64_tr_b16 v[170:171], v0 offset:0x2e00
	s_waitcnt lgkmcnt(10)
	v_mfma_f32_32x32x16_bf16 v[128:143], v[208:211], v[148:151], v[128:143]
	v_mfma_f32_32x32x16_bf16 v[96:111], v[10:13], v[148:151], v[96:111]
	ds_read_b64_tr_b16 v[172:173], v0 offset:0x3600
	ds_read_b64_tr_b16 v[174:175], v0 offset:0x3e00
	s_waitcnt lgkmcnt(10)
	v_mfma_f32_32x32x16_bf16 v[112:127], v[6:9], v[152:155], v[112:127]
	v_mfma_f32_32x32x16_bf16 v[80:95], v[2:5], v[152:155], v[80:95]
	s_waitcnt lgkmcnt(8)
	v_mfma_f32_32x32x16_bf16 v[112:127], v[208:211], v[156:159], v[112:127]
	v_mfma_f32_32x32x16_bf16 v[80:95], v[10:13], v[156:159], v[80:95]
	s_waitcnt lgkmcnt(6)
	v_mfma_f32_32x32x16_bf16 v[64:79], v[6:9], v[160:163], v[64:79]
	v_mfma_f32_32x32x16_bf16 v[32:47], v[2:5], v[160:163], v[32:47]
	s_waitcnt lgkmcnt(4)
	v_mfma_f32_32x32x16_bf16 v[64:79], v[208:211], v[164:167], v[64:79]
	v_mfma_f32_32x32x16_bf16 v[32:47], v[10:13], v[164:167], v[32:47]
	s_waitcnt lgkmcnt(2)
	v_mfma_f32_32x32x16_bf16 v[48:63], v[6:9], v[168:171], v[48:63]
	v_mfma_f32_32x32x16_bf16 v[16:31], v[2:5], v[168:171], v[16:31]
	s_waitcnt lgkmcnt(0)
	v_mfma_f32_32x32x16_bf16 v[48:63], v[208:211], v[172:175], v[48:63]
	v_mfma_f32_32x32x16_bf16 v[16:31], v[10:13], v[172:175], v[16:31]

.LBB0_1249:
	s_cmp_eq_u32 s86, 0
	s_cselect_b64 s[0:1], -1, 0
	s_or_b64 s[0:1], s[88:89], s[0:1]
	s_and_b64 vcc, exec, s[0:1]
	s_cbranch_vccnz .LBB0_1251
	s_add_i32 s0, s77, 0xc000
	s_and_b32 s0, s0, 0xc000
	v_add_u32_e32 v0, s0, v234
	ds_read_b64_tr_b16 v[144:145], v0 offset:0x2000
	ds_read_b64_tr_b16 v[146:147], v0 offset:0x2800
	ds_read_b64_tr_b16 v[148:149], v0 offset:0x3000
	ds_read_b64_tr_b16 v[150:151], v0 offset:0x3800
	ds_read_b64_tr_b16 v[152:153], v0 offset:0x2200
	ds_read_b64_tr_b16 v[154:155], v0 offset:0x2a00
	ds_read_b64_tr_b16 v[156:157], v0 offset:0x3200
	ds_read_b64_tr_b16 v[158:159], v0 offset:0x3a00
	ds_read_b64_tr_b16 v[160:161], v0 offset:0x2400
	ds_read_b64_tr_b16 v[162:163], v0 offset:0x2c00
	ds_read_b64_tr_b16 v[164:165], v0 offset:0x3400
	ds_read_b64_tr_b16 v[166:167], v0 offset:0x3c00
	s_waitcnt lgkmcnt(10)
	s_nop 0
	v_mfma_f32_32x32x16_bf16 v[128:143], v[6:9], v[144:147], v[128:143]
	v_mfma_f32_32x32x16_bf16 v[96:111], v[2:5], v[144:147], v[96:111]
	ds_read_b64_tr_b16 v[168:169], v0 offset:0x2600
	ds_read_b64_tr_b16 v[170:171], v0 offset:0x2e00
	s_waitcnt lgkmcnt(10)
	v_mfma_f32_32x32x16_bf16 v[128:143], v[208:211], v[148:151], v[128:143]
	v_mfma_f32_32x32x16_bf16 v[96:111], v[10:13], v[148:151], v[96:111]
	ds_read_b64_tr_b16 v[172:173], v0 offset:0x3600
	ds_read_b64_tr_b16 v[174:175], v0 offset:0x3e00
	s_waitcnt lgkmcnt(10)
	v_mfma_f32_32x32x16_bf16 v[112:127], v[6:9], v[152:155], v[112:127]
	v_mfma_f32_32x32x16_bf16 v[80:95], v[2:5], v[152:155], v[80:95]
	s_waitcnt lgkmcnt(8)
	v_mfma_f32_32x32x16_bf16 v[112:127], v[208:211], v[156:159], v[112:127]
	v_mfma_f32_32x32x16_bf16 v[80:95], v[10:13], v[156:159], v[80:95]
	s_waitcnt lgkmcnt(6)
	v_mfma_f32_32x32x16_bf16 v[64:79], v[6:9], v[160:163], v[64:79]
	v_mfma_f32_32x32x16_bf16 v[48:63], v[2:5], v[160:163], v[48:63]
	s_waitcnt lgkmcnt(4)
	v_mfma_f32_32x32x16_bf16 v[64:79], v[208:211], v[164:167], v[64:79]
	v_mfma_f32_32x32x16_bf16 v[48:63], v[10:13], v[164:167], v[48:63]
	s_waitcnt lgkmcnt(2)
	v_mfma_f32_32x32x16_bf16 v[32:47], v[6:9], v[168:171], v[32:47]
	v_mfma_f32_32x32x16_bf16 v[16:31], v[2:5], v[168:171], v[16:31]
	s_waitcnt lgkmcnt(0)
	v_mfma_f32_32x32x16_bf16 v[32:47], v[208:211], v[172:175], v[32:47]
	v_mfma_f32_32x32x16_bf16 v[16:31], v[10:13], v[172:175], v[16:31]

.LBB0_1267:
	v_add_u32_e32 v242, s27, v234
	ds_read_b64_tr_b16 v[144:145], v242 offset:0
	ds_read_b64_tr_b16 v[146:147], v242 offset:0x800
	ds_read_b64_tr_b16 v[148:149], v242 offset:0x1000
	ds_read_b64_tr_b16 v[150:151], v242 offset:0x1800
	ds_read_b64_tr_b16 v[152:153], v242 offset:0x200
	ds_read_b64_tr_b16 v[154:155], v242 offset:0xa00
	ds_read_b64_tr_b16 v[156:157], v242 offset:0x1200
	ds_read_b64_tr_b16 v[158:159], v242 offset:0x1a00
	ds_read_b64_tr_b16 v[160:161], v242 offset:0x400
	ds_read_b64_tr_b16 v[162:163], v242 offset:0xc00
	ds_read_b64_tr_b16 v[164:165], v242 offset:0x1400
	ds_read_b64_tr_b16 v[166:167], v242 offset:0x1c00
	s_waitcnt lgkmcnt(10)
	s_nop 0
	v_mfma_f32_32x32x16_bf16 v[128:143], v[216:219], v[144:147], v[128:143]
	v_mfma_f32_32x32x16_bf16 v[96:111], v[212:215], v[144:147], v[96:111]
	ds_read_b64_tr_b16 v[168:169], v242 offset:0x600
	ds_read_b64_tr_b16 v[170:171], v242 offset:0xe00
	s_waitcnt lgkmcnt(10)
	v_mfma_f32_32x32x16_bf16 v[128:143], v[224:227], v[148:151], v[128:143]
	v_mfma_f32_32x32x16_bf16 v[96:111], v[220:223], v[148:151], v[96:111]
	ds_read_b64_tr_b16 v[172:173], v242 offset:0x1600
	ds_read_b64_tr_b16 v[174:175], v242 offset:0x1e00
	s_waitcnt lgkmcnt(10)
	v_mfma_f32_32x32x16_bf16 v[112:127], v[216:219], v[152:155], v[112:127]
	v_mfma_f32_32x32x16_bf16 v[80:95], v[212:215], v[152:155], v[80:95]
	s_waitcnt lgkmcnt(8)
	v_mfma_f32_32x32x16_bf16 v[112:127], v[224:227], v[156:159], v[112:127]
	v_mfma_f32_32x32x16_bf16 v[80:95], v[220:223], v[156:159], v[80:95]
	ds_read_b128 v[144:147], v241 offset:0x2000
	ds_read_b128 v[148:151], v240 offset:0x2000
	ds_read_b128 v[152:155], v239 offset:0x2000
	ds_read_b128 v[156:159], v0 offset:0x2000
	s_waitcnt lgkmcnt(10)
	v_mfma_f32_32x32x16_bf16 v[64:79], v[216:219], v[160:163], v[64:79]
	v_mfma_f32_32x32x16_bf16 v[48:63], v[212:215], v[160:163], v[48:63]
	s_waitcnt lgkmcnt(8)
	v_mfma_f32_32x32x16_bf16 v[64:79], v[224:227], v[164:167], v[64:79]
	v_mfma_f32_32x32x16_bf16 v[48:63], v[220:223], v[164:167], v[48:63]
	s_waitcnt lgkmcnt(6)
	v_mfma_f32_32x32x16_bf16 v[32:47], v[216:219], v[168:171], v[32:47]
	v_mfma_f32_32x32x16_bf16 v[16:31], v[212:215], v[168:171], v[16:31]
	s_waitcnt lgkmcnt(4)
	v_mfma_f32_32x32x16_bf16 v[32:47], v[224:227], v[172:175], v[32:47]
	v_mfma_f32_32x32x16_bf16 v[16:31], v[220:223], v[172:175], v[16:31]
	s_waitcnt lgkmcnt(0)
	s_waitcnt lgkmcnt(0)
	v_mfma_f32_32x32x16_bf16 v[160:175], v[144:147], v[176:179], 0
	v_cmp_eq_f32_e32 vcc, 0, v238
	s_cmp_eq_u64 vcc, exec
	v_mfma_f32_32x32x16_bf16 v[160:175], v[148:151], v[180:183], v[160:175]
	v_mfma_f32_32x32x16_bf16 v[160:175], v[152:155], v[184:187], v[160:175]
	v_mfma_f32_32x32x16_bf16 v[160:175], v[156:159], v[188:191], v[160:175]
	s_cbranch_scc0 .LBB0_1297

.LBB0_1283:
	s_andn2_b64 vcc, exec, s[84:85]
	s_cbranch_vccnz .LBB0_1242
	ds_read_b64_tr_b16 v[144:145], v242 offset:0x2000
	ds_read_b64_tr_b16 v[146:147], v242 offset:0x2800
	ds_read_b64_tr_b16 v[148:149], v242 offset:0x3000
	ds_read_b64_tr_b16 v[150:151], v242 offset:0x3800
	ds_read_b64_tr_b16 v[152:153], v242 offset:0x2200
	ds_read_b64_tr_b16 v[154:155], v242 offset:0x2a00
	ds_read_b64_tr_b16 v[156:157], v242 offset:0x3200
	ds_read_b64_tr_b16 v[158:159], v242 offset:0x3a00
	ds_read_b64_tr_b16 v[160:161], v242 offset:0x2400
	ds_read_b64_tr_b16 v[162:163], v242 offset:0x2c00
	ds_read_b64_tr_b16 v[164:165], v242 offset:0x3400
	ds_read_b64_tr_b16 v[166:167], v242 offset:0x3c00
	s_waitcnt lgkmcnt(10)
	s_nop 0
	v_mfma_f32_32x32x16_bf16 v[128:143], v[6:9], v[144:147], v[128:143]
	v_mfma_f32_32x32x16_bf16 v[96:111], v[2:5], v[144:147], v[96:111]
	ds_read_b64_tr_b16 v[168:169], v242 offset:0x2600
	ds_read_b64_tr_b16 v[170:171], v242 offset:0x2e00
	s_waitcnt lgkmcnt(10)
	v_mfma_f32_32x32x16_bf16 v[128:143], v[208:211], v[148:151], v[128:143]
	v_mfma_f32_32x32x16_bf16 v[96:111], v[10:13], v[148:151], v[96:111]
	ds_read_b64_tr_b16 v[172:173], v242 offset:0x3600
	ds_read_b64_tr_b16 v[174:175], v242 offset:0x3e00
	s_waitcnt lgkmcnt(10)
	v_mfma_f32_32x32x16_bf16 v[112:127], v[6:9], v[152:155], v[112:127]
	v_mfma_f32_32x32x16_bf16 v[80:95], v[2:5], v[152:155], v[80:95]
	s_waitcnt lgkmcnt(8)
	v_mfma_f32_32x32x16_bf16 v[112:127], v[208:211], v[156:159], v[112:127]
	v_mfma_f32_32x32x16_bf16 v[80:95], v[10:13], v[156:159], v[80:95]
	s_waitcnt lgkmcnt(6)
	v_mfma_f32_32x32x16_bf16 v[64:79], v[6:9], v[160:163], v[64:79]
	v_mfma_f32_32x32x16_bf16 v[48:63], v[2:5], v[160:163], v[48:63]
	s_waitcnt lgkmcnt(4)
	v_mfma_f32_32x32x16_bf16 v[64:79], v[208:211], v[164:167], v[64:79]
	v_mfma_f32_32x32x16_bf16 v[48:63], v[10:13], v[164:167], v[48:63]
	s_waitcnt lgkmcnt(2)
	v_mfma_f32_32x32x16_bf16 v[32:47], v[6:9], v[168:171], v[32:47]
	v_mfma_f32_32x32x16_bf16 v[16:31], v[2:5], v[168:171], v[16:31]
	s_waitcnt lgkmcnt(0)
	v_mfma_f32_32x32x16_bf16 v[32:47], v[208:211], v[172:175], v[32:47]
	v_mfma_f32_32x32x16_bf16 v[16:31], v[10:13], v[172:175], v[16:31]
	s_branch .LBB0_1242

.LBB0_1317:
	s_and_b64 vcc, exec, s[34:35]
	s_cbranch_vccz .LBB0_1319
	s_cmp_lg_u32 0, -1
	s_cselect_b32 s0, 0, 0
	s_add_i32 s0, s0, 0xc000
	v_add_u32_e32 v0, s0, v232
	ds_read_b64_tr_b16 v[144:145], v0 offset:0x2000
	ds_read_b64_tr_b16 v[146:147], v0 offset:0x2800
	ds_read_b64_tr_b16 v[148:149], v0 offset:0x3000
	ds_read_b64_tr_b16 v[150:151], v0 offset:0x3800
	ds_read_b64_tr_b16 v[152:153], v0 offset:0x2200
	ds_read_b64_tr_b16 v[154:155], v0 offset:0x2a00
	ds_read_b64_tr_b16 v[156:157], v0 offset:0x3200
	ds_read_b64_tr_b16 v[158:159], v0 offset:0x3a00
	ds_read_b64_tr_b16 v[160:161], v0 offset:0x2400
	ds_read_b64_tr_b16 v[162:163], v0 offset:0x2c00
	ds_read_b64_tr_b16 v[164:165], v0 offset:0x3400
	ds_read_b64_tr_b16 v[166:167], v0 offset:0x3c00
	s_waitcnt lgkmcnt(10)
	s_nop 0
	v_mfma_f32_32x32x16_bf16 v[128:143], v[6:9], v[144:147], v[128:143]
	v_mfma_f32_32x32x16_bf16 v[96:111], v[2:5], v[144:147], v[96:111]
	ds_read_b64_tr_b16 v[168:169], v0 offset:0x2600
	ds_read_b64_tr_b16 v[170:171], v0 offset:0x2e00
	s_waitcnt lgkmcnt(10)
	v_mfma_f32_32x32x16_bf16 v[128:143], v[208:211], v[148:151], v[128:143]
	v_mfma_f32_32x32x16_bf16 v[96:111], v[10:13], v[148:151], v[96:111]
	ds_read_b64_tr_b16 v[172:173], v0 offset:0x3600
	ds_read_b64_tr_b16 v[174:175], v0 offset:0x3e00
	s_waitcnt lgkmcnt(10)
	v_mfma_f32_32x32x16_bf16 v[112:127], v[6:9], v[152:155], v[112:127]
	v_mfma_f32_32x32x16_bf16 v[80:95], v[2:5], v[152:155], v[80:95]
	s_waitcnt lgkmcnt(8)
	v_mfma_f32_32x32x16_bf16 v[112:127], v[208:211], v[156:159], v[112:127]
	v_mfma_f32_32x32x16_bf16 v[80:95], v[10:13], v[156:159], v[80:95]
	s_waitcnt lgkmcnt(6)
	v_mfma_f32_32x32x16_bf16 v[64:79], v[6:9], v[160:163], v[64:79]
	v_mfma_f32_32x32x16_bf16 v[48:63], v[2:5], v[160:163], v[48:63]
	s_waitcnt lgkmcnt(4)
	v_mfma_f32_32x32x16_bf16 v[64:79], v[208:211], v[164:167], v[64:79]
	v_mfma_f32_32x32x16_bf16 v[48:63], v[10:13], v[164:167], v[48:63]
	s_waitcnt lgkmcnt(2)
	v_mfma_f32_32x32x16_bf16 v[32:47], v[6:9], v[168:171], v[32:47]
	v_mfma_f32_32x32x16_bf16 v[16:31], v[2:5], v[168:171], v[16:31]
	s_waitcnt lgkmcnt(0)
	v_mfma_f32_32x32x16_bf16 v[32:47], v[208:211], v[172:175], v[32:47]
	v_mfma_f32_32x32x16_bf16 v[16:31], v[10:13], v[172:175], v[16:31]

.LBB0_2103:
	s_cmp_eq_u32 s58, 0
	s_cselect_b64 s[0:1], -1, 0
	s_or_b64 s[0:1], s[60:61], s[0:1]
	s_and_b64 vcc, exec, s[0:1]
	s_cbranch_vccnz .LBB0_2105
	s_add_i32 s0, s68, 0xc000
	s_and_b32 s0, s0, 0xc000
	v_add_u32_e32 v0, s0, v234
	ds_read_b64_tr_b16 v[144:145], v0 offset:0x2000
	ds_read_b64_tr_b16 v[146:147], v0 offset:0x2800
	ds_read_b64_tr_b16 v[148:149], v0 offset:0x3000
	ds_read_b64_tr_b16 v[150:151], v0 offset:0x3800
	ds_read_b64_tr_b16 v[152:153], v0 offset:0x2200
	ds_read_b64_tr_b16 v[154:155], v0 offset:0x2a00
	ds_read_b64_tr_b16 v[156:157], v0 offset:0x3200
	ds_read_b64_tr_b16 v[158:159], v0 offset:0x3a00
	ds_read_b64_tr_b16 v[160:161], v0 offset:0x2400
	ds_read_b64_tr_b16 v[162:163], v0 offset:0x2c00
	ds_read_b64_tr_b16 v[164:165], v0 offset:0x3400
	ds_read_b64_tr_b16 v[166:167], v0 offset:0x3c00
	s_waitcnt lgkmcnt(10)
	s_nop 0
	v_mfma_f32_32x32x16_bf16 v[128:143], v[6:9], v[144:147], v[128:143]
	v_mfma_f32_32x32x16_bf16 v[96:111], v[2:5], v[144:147], v[96:111]
	ds_read_b64_tr_b16 v[168:169], v0 offset:0x2600
	ds_read_b64_tr_b16 v[170:171], v0 offset:0x2e00
	s_waitcnt lgkmcnt(10)
	v_mfma_f32_32x32x16_bf16 v[128:143], v[208:211], v[148:151], v[128:143]
	v_mfma_f32_32x32x16_bf16 v[96:111], v[10:13], v[148:151], v[96:111]
	ds_read_b64_tr_b16 v[172:173], v0 offset:0x3600
	ds_read_b64_tr_b16 v[174:175], v0 offset:0x3e00
	s_waitcnt lgkmcnt(10)
	v_mfma_f32_32x32x16_bf16 v[112:127], v[6:9], v[152:155], v[112:127]
	v_mfma_f32_32x32x16_bf16 v[80:95], v[2:5], v[152:155], v[80:95]
	s_waitcnt lgkmcnt(8)
	v_mfma_f32_32x32x16_bf16 v[112:127], v[208:211], v[156:159], v[112:127]
	v_mfma_f32_32x32x16_bf16 v[80:95], v[10:13], v[156:159], v[80:95]
	s_waitcnt lgkmcnt(6)
	v_mfma_f32_32x32x16_bf16 v[64:79], v[6:9], v[160:163], v[64:79]
	v_mfma_f32_32x32x16_bf16 v[32:47], v[2:5], v[160:163], v[32:47]
	s_waitcnt lgkmcnt(4)
	v_mfma_f32_32x32x16_bf16 v[64:79], v[208:211], v[164:167], v[64:79]
	v_mfma_f32_32x32x16_bf16 v[32:47], v[10:13], v[164:167], v[32:47]
	s_waitcnt lgkmcnt(2)
	v_mfma_f32_32x32x16_bf16 v[48:63], v[6:9], v[168:171], v[48:63]
	v_mfma_f32_32x32x16_bf16 v[16:31], v[2:5], v[168:171], v[16:31]
	s_waitcnt lgkmcnt(0)
	v_mfma_f32_32x32x16_bf16 v[48:63], v[208:211], v[172:175], v[48:63]
	v_mfma_f32_32x32x16_bf16 v[16:31], v[10:13], v[172:175], v[16:31]

.LBB0_2121:
	v_add_u32_e32 v242, s27, v234
	ds_read_b64_tr_b16 v[144:145], v242 offset:0
	ds_read_b64_tr_b16 v[146:147], v242 offset:0x800
	ds_read_b64_tr_b16 v[148:149], v242 offset:0x1000
	ds_read_b64_tr_b16 v[150:151], v242 offset:0x1800
	ds_read_b64_tr_b16 v[152:153], v242 offset:0x200
	ds_read_b64_tr_b16 v[154:155], v242 offset:0xa00
	ds_read_b64_tr_b16 v[156:157], v242 offset:0x1200
	ds_read_b64_tr_b16 v[158:159], v242 offset:0x1a00
	ds_read_b64_tr_b16 v[160:161], v242 offset:0x400
	ds_read_b64_tr_b16 v[162:163], v242 offset:0xc00
	ds_read_b64_tr_b16 v[164:165], v242 offset:0x1400
	ds_read_b64_tr_b16 v[166:167], v242 offset:0x1c00
	s_waitcnt lgkmcnt(10)
	s_nop 0
	v_mfma_f32_32x32x16_bf16 v[128:143], v[216:219], v[144:147], v[128:143]
	v_mfma_f32_32x32x16_bf16 v[96:111], v[212:215], v[144:147], v[96:111]
	ds_read_b64_tr_b16 v[168:169], v242 offset:0x600
	ds_read_b64_tr_b16 v[170:171], v242 offset:0xe00
	s_waitcnt lgkmcnt(10)
	v_mfma_f32_32x32x16_bf16 v[128:143], v[224:227], v[148:151], v[128:143]
	v_mfma_f32_32x32x16_bf16 v[96:111], v[220:223], v[148:151], v[96:111]
	ds_read_b64_tr_b16 v[172:173], v242 offset:0x1600
	ds_read_b64_tr_b16 v[174:175], v242 offset:0x1e00
	s_waitcnt lgkmcnt(10)
	v_mfma_f32_32x32x16_bf16 v[112:127], v[216:219], v[152:155], v[112:127]
	v_mfma_f32_32x32x16_bf16 v[80:95], v[212:215], v[152:155], v[80:95]
	s_waitcnt lgkmcnt(8)
	v_mfma_f32_32x32x16_bf16 v[112:127], v[224:227], v[156:159], v[112:127]
	v_mfma_f32_32x32x16_bf16 v[80:95], v[220:223], v[156:159], v[80:95]
	ds_read_b128 v[144:147], v241 offset:0x2000
	ds_read_b128 v[148:151], v240 offset:0x2000
	ds_read_b128 v[156:159], v239 offset:0x2000
	ds_read_b128 v[244:247], v0 offset:0x2000
	s_waitcnt lgkmcnt(10)
	v_mfma_f32_32x32x16_bf16 v[64:79], v[216:219], v[160:163], v[64:79]
	v_mfma_f32_32x32x16_bf16 v[32:47], v[212:215], v[160:163], v[32:47]
	s_waitcnt lgkmcnt(8)
	v_mfma_f32_32x32x16_bf16 v[64:79], v[224:227], v[164:167], v[64:79]
	v_mfma_f32_32x32x16_bf16 v[32:47], v[220:223], v[164:167], v[32:47]
	s_waitcnt lgkmcnt(6)
	v_mfma_f32_32x32x16_bf16 v[48:63], v[216:219], v[168:171], v[48:63]
	v_mfma_f32_32x32x16_bf16 v[16:31], v[212:215], v[168:171], v[16:31]
	s_waitcnt lgkmcnt(4)
	v_mfma_f32_32x32x16_bf16 v[48:63], v[224:227], v[172:175], v[48:63]
	v_mfma_f32_32x32x16_bf16 v[16:31], v[220:223], v[172:175], v[16:31]
	s_waitcnt lgkmcnt(0)
	v_mfma_f32_32x32x16_bf16 v[160:175], v[144:147], v[176:179], 0
	v_cmp_eq_f32_e32 vcc, 0, v238
	s_cmp_eq_u64 vcc, exec
	v_mfma_f32_32x32x16_bf16 v[160:175], v[148:151], v[180:183], v[160:175]
	v_mfma_f32_32x32x16_bf16 v[160:175], v[156:159], v[184:187], v[160:175]
	v_mfma_f32_32x32x16_bf16 v[160:175], v[244:247], v[188:191], v[160:175]
	s_cbranch_scc0 .LBB0_2151

.LBB0_2137:
	s_andn2_b64 vcc, exec, s[52:53]
	s_cbranch_vccnz .LBB0_2096
	ds_read_b64_tr_b16 v[144:145], v242 offset:0x2000
	ds_read_b64_tr_b16 v[146:147], v242 offset:0x2800
	ds_read_b64_tr_b16 v[148:149], v242 offset:0x3000
	ds_read_b64_tr_b16 v[150:151], v242 offset:0x3800
	ds_read_b64_tr_b16 v[152:153], v242 offset:0x2200
	ds_read_b64_tr_b16 v[154:155], v242 offset:0x2a00
	ds_read_b64_tr_b16 v[156:157], v242 offset:0x3200
	ds_read_b64_tr_b16 v[158:159], v242 offset:0x3a00
	ds_read_b64_tr_b16 v[160:161], v242 offset:0x2400
	ds_read_b64_tr_b16 v[162:163], v242 offset:0x2c00
	ds_read_b64_tr_b16 v[164:165], v242 offset:0x3400
	ds_read_b64_tr_b16 v[166:167], v242 offset:0x3c00
	s_waitcnt lgkmcnt(10)
	s_nop 0
	v_mfma_f32_32x32x16_bf16 v[128:143], v[6:9], v[144:147], v[128:143]
	v_mfma_f32_32x32x16_bf16 v[96:111], v[2:5], v[144:147], v[96:111]
	ds_read_b64_tr_b16 v[168:169], v242 offset:0x2600
	ds_read_b64_tr_b16 v[170:171], v242 offset:0x2e00
	s_waitcnt lgkmcnt(10)
	v_mfma_f32_32x32x16_bf16 v[128:143], v[208:211], v[148:151], v[128:143]
	v_mfma_f32_32x32x16_bf16 v[96:111], v[10:13], v[148:151], v[96:111]
	ds_read_b64_tr_b16 v[172:173], v242 offset:0x3600
	ds_read_b64_tr_b16 v[174:175], v242 offset:0x3e00
	s_waitcnt lgkmcnt(10)
	v_mfma_f32_32x32x16_bf16 v[112:127], v[6:9], v[152:155], v[112:127]
	v_mfma_f32_32x32x16_bf16 v[80:95], v[2:5], v[152:155], v[80:95]
	s_waitcnt lgkmcnt(8)
	v_mfma_f32_32x32x16_bf16 v[112:127], v[208:211], v[156:159], v[112:127]
	v_mfma_f32_32x32x16_bf16 v[80:95], v[10:13], v[156:159], v[80:95]
	s_waitcnt lgkmcnt(6)
	v_mfma_f32_32x32x16_bf16 v[64:79], v[6:9], v[160:163], v[64:79]
	v_mfma_f32_32x32x16_bf16 v[32:47], v[2:5], v[160:163], v[32:47]
	s_waitcnt lgkmcnt(4)
	v_mfma_f32_32x32x16_bf16 v[64:79], v[208:211], v[164:167], v[64:79]
	v_mfma_f32_32x32x16_bf16 v[32:47], v[10:13], v[164:167], v[32:47]
	s_waitcnt lgkmcnt(2)
	v_mfma_f32_32x32x16_bf16 v[48:63], v[6:9], v[168:171], v[48:63]
	v_mfma_f32_32x32x16_bf16 v[16:31], v[2:5], v[168:171], v[16:31]
	s_waitcnt lgkmcnt(0)
	v_mfma_f32_32x32x16_bf16 v[48:63], v[208:211], v[172:175], v[48:63]
	v_mfma_f32_32x32x16_bf16 v[16:31], v[10:13], v[172:175], v[16:31]
	s_branch .LBB0_2096

.LBB0_2171:
	s_and_b64 vcc, exec, s[42:43]
	s_cbranch_vccz .LBB0_2173
	s_cmp_lg_u32 0, -1
	s_cselect_b32 s0, 0, 0
	s_add_i32 s0, s0, 0xc000
	v_add_u32_e32 v0, s0, v232
	ds_read_b64_tr_b16 v[144:145], v0 offset:0x2000
	ds_read_b64_tr_b16 v[146:147], v0 offset:0x2800
	ds_read_b64_tr_b16 v[148:149], v0 offset:0x3000
	ds_read_b64_tr_b16 v[150:151], v0 offset:0x3800
	ds_read_b64_tr_b16 v[152:153], v0 offset:0x2200
	ds_read_b64_tr_b16 v[154:155], v0 offset:0x2a00
	ds_read_b64_tr_b16 v[156:157], v0 offset:0x3200
	ds_read_b64_tr_b16 v[158:159], v0 offset:0x3a00
	ds_read_b64_tr_b16 v[160:161], v0 offset:0x2400
	ds_read_b64_tr_b16 v[162:163], v0 offset:0x2c00
	ds_read_b64_tr_b16 v[164:165], v0 offset:0x3400
	ds_read_b64_tr_b16 v[166:167], v0 offset:0x3c00
	s_waitcnt lgkmcnt(10)
	s_nop 0
	v_mfma_f32_32x32x16_bf16 v[128:143], v[6:9], v[144:147], v[128:143]
	v_mfma_f32_32x32x16_bf16 v[96:111], v[2:5], v[144:147], v[96:111]
	ds_read_b64_tr_b16 v[168:169], v0 offset:0x2600
	ds_read_b64_tr_b16 v[170:171], v0 offset:0x2e00
	s_waitcnt lgkmcnt(10)
	v_mfma_f32_32x32x16_bf16 v[128:143], v[208:211], v[148:151], v[128:143]
	v_mfma_f32_32x32x16_bf16 v[96:111], v[10:13], v[148:151], v[96:111]
	ds_read_b64_tr_b16 v[172:173], v0 offset:0x3600
	ds_read_b64_tr_b16 v[174:175], v0 offset:0x3e00
	s_waitcnt lgkmcnt(10)
	v_mfma_f32_32x32x16_bf16 v[112:127], v[6:9], v[152:155], v[112:127]
	v_mfma_f32_32x32x16_bf16 v[80:95], v[2:5], v[152:155], v[80:95]
	s_waitcnt lgkmcnt(8)
	v_mfma_f32_32x32x16_bf16 v[112:127], v[208:211], v[156:159], v[112:127]
	v_mfma_f32_32x32x16_bf16 v[80:95], v[10:13], v[156:159], v[80:95]
	s_waitcnt lgkmcnt(6)
	v_mfma_f32_32x32x16_bf16 v[64:79], v[6:9], v[160:163], v[64:79]
	v_mfma_f32_32x32x16_bf16 v[32:47], v[2:5], v[160:163], v[32:47]
	s_waitcnt lgkmcnt(4)
	v_mfma_f32_32x32x16_bf16 v[64:79], v[208:211], v[164:167], v[64:79]
	v_mfma_f32_32x32x16_bf16 v[32:47], v[10:13], v[164:167], v[32:47]
	s_waitcnt lgkmcnt(2)
	v_mfma_f32_32x32x16_bf16 v[48:63], v[6:9], v[168:171], v[48:63]
	v_mfma_f32_32x32x16_bf16 v[16:31], v[2:5], v[168:171], v[16:31]
	s_waitcnt lgkmcnt(0)
	v_mfma_f32_32x32x16_bf16 v[48:63], v[208:211], v[172:175], v[48:63]
	v_mfma_f32_32x32x16_bf16 v[16:31], v[10:13], v[172:175], v[16:31]
